# attention unit->workgroup remap for diff and MLA: the 16 query blocks of one (batch, head) now run concurrently on 16 workgroups of the same XCD (was 4 / 2), so each K/V stream is fetched into that XC
# speedup vs baseline: 1.0029x; 1.0024x over previous
.LBB0_657:
	s_add_i32 s2, s14, s55
	s_cmp_lg_u32 s74, 0x100
	s_cbranch_scc1 .Lmmap_old
	s_lshr_b32 s4, s55, 3
	s_and_b32 s5, s4, 15
	s_bfe_u32 s19, s4, 0x10004
	s_lshr_b32 s4, s4, 5
	s_lshl_b32 s4, s4, 4
	s_lshl_b32 s2, s14, 1
	s_add_i32 s4, s4, s2
	s_add_i32 s4, s4, s19
	s_lshl_b32 s4, s4, 4
	s_or_b32 s2, s4, s5
.Lmmap_old:
	s_mov_b32 s18, s2
	s_cmpk_gt_i32 s2, 0x7ff
	s_mov_b64 s[0:1], -1
	s_cbranch_scc1 .LBB0_656
	s_ashr_i32 s4, s2, 8
	s_bfe_u32 s19, s2, 0x40004
	v_mov_b32_e32 v0, v194
	s_ashr_i32 s5, s4, 31
	s_lshl_b32 s2, s2, 8
	s_lshl_b64 s[0:1], s[4:5], 12
	s_and_b32 s2, s2, 0xf00
	v_ashrrev_i32_e32 v2, 1, v0
	s_or_b32 s0, s0, s2
	v_and_b32_e32 v2, 0xffffffe0, v2
	v_ashrrev_i32_e32 v3, 31, v2
	v_and_or_b32 v4, v0, 31, s0
	v_mov_b32_e32 v5, s1
	v_lshl_add_u64 v[126:127], v[4:5], 0, v[2:3]
	v_mov_b64_e32 v[2:3], s[56:57]
	s_movk_i32 s2, 0xc00
	v_mad_u64_u32 v[2:3], s[0:1], v126, s2, v[2:3]
	v_bfe_u32 v132, v0, 5, 1
	v_mad_i32_i24 v3, v127, s2, v3
	s_mul_i32 s90, s19, 0xc0
	s_lshl_b64 s[0:1], s[4:5], 24
	s_lshl_b64 s[6:7], s[4:5], 18
	v_readlane_b32 s2, v254, 61
	v_lshl_add_u64 v[2:3], v[2:3], 0, s[90:91]
	v_lshlrev_b32_e32 v0, 4, v132
	v_readlane_b32 s3, v254, 62
	s_add_u32 s8, s2, s6
	v_lshl_add_u64 v[2:3], v[2:3], 0, v[0:1]
	s_addc_u32 s9, s3, s7
	global_load_dwordx4 v[82:85], v[2:3], off
	global_load_dwordx4 v[86:89], v[2:3], off offset:32
	global_load_dwordx4 v[90:93], v[2:3], off offset:64
	global_load_dwordx4 v[94:97], v[2:3], off offset:96
	global_load_dwordx4 v[98:101], v[2:3], off offset:128
	global_load_dwordx4 v[102:105], v[2:3], off offset:160
	s_add_u32 s2, s58, s0
	v_mov_b32_e32 v14, v194
	s_addc_u32 s3, s59, s1
	s_lshl_b32 s4, s19, 8
	s_add_u32 s10, s2, s4
	v_ashrrev_i32_e32 v11, 2, v14
	v_lshlrev_b32_e32 v10, 4, v14
	v_and_b32_e32 v133, 0x70, v10
	v_lshlrev_b32_e32 v0, 11, v11
	s_movk_i32 s2, 0xf000
	s_addc_u32 s11, s3, 0
	v_and_or_b32 v0, v0, s2, v133
	v_add_u32_e32 v241, 0x20000, v0
	global_load_dwordx4 v[2:5], v241, s[10:11]
	s_mov_b32 s100, 0xfffe0000
	s_mov_b32 s101, -1
	v_lshl_add_u64 v[246:247], s[10:11], 0, v[0:1]
	v_lshl_add_u64 v[246:247], v[246:247], 0, s[100:101]
	global_load_dwordx4 v[248:251], v[246:247], off
	s_movk_i32 s2, 0xff
	v_cmp_lt_i32_e64 s[4:5], s2, v14
	s_movk_i32 s2, 0x100
	v_cmp_gt_i32_e64 s[2:3], s2, v14
	s_and_saveexec_b64 s[16:17], s[2:3]
	s_cbranch_execz .LBB0_660
	v_add_u32_e32 v244, 0x800, v10
	global_load_dwordx4 v[106:109], v244, s[8:9]
	v_mov_b32_e32 v252, v10
	v_mov_b32_e32 v253, 0
	v_lshl_add_u64 v[252:253], s[8:9], 0, v[252:253]
	s_mov_b32 s98, 0xfffff800
	s_mov_b32 s99, -1
	v_lshl_add_u64 v[252:253], v[252:253], 0, s[98:99]
	global_load_dwordx4 v[236:239], v[252:253], off

.LBB0_797:
	s_add_i32 s4, s14, s48
	s_cmp_lg_u32 s74, 0x100
	s_cbranch_scc1 .Ldmap_old
	s_lshr_b32 s2, s48, 2
	s_and_b32 s3, s2, 15
	s_bfe_u32 s5, s2, 0x10004
	s_lshr_b32 s2, s2, 5
	s_lshl_b32 s2, s2, 3
	s_lshl_b32 s6, s14, 1
	s_add_i32 s2, s2, s6
	s_add_i32 s2, s2, s5
	s_lshl_b32 s2, s2, 4
	s_or_b32 s4, s2, s3
.Ldmap_old:
	s_cmpk_gt_i32 s4, 0x3ff
	s_mov_b64 s[2:3], -1
	s_cbranch_scc1 .LBB0_796
	s_bfe_u32 s2, s4, 0x30004
	s_lshl_b32 s24, s2, 7
	s_lshl_b32 s8, s2, 8
	s_ashr_i32 s2, s4, 7
	s_ashr_i32 s3, s2, 31
	v_mov_b32_e32 v0, v194
	s_lshl_b64 s[6:7], s[2:3], 12
	s_lshl_b32 s3, s4, 8
	s_and_b32 s3, s3, 0xf00
	v_ashrrev_i32_e32 v2, 1, v0
	s_or_b32 s3, s6, s3
	v_and_b32_e32 v2, 0xffffffe0, v2
	v_ashrrev_i32_e32 v3, 31, v2
	v_and_or_b32 v4, v0, 31, s3
	v_mov_b32_e32 v5, s7
	v_lshl_add_u64 v[184:185], v[4:5], 0, v[2:3]
	v_mov_b64_e32 v[2:3], s[56:57]
	v_mad_u64_u32 v[2:3], s[6:7], v184, s87, v[2:3]
	s_add_i32 s3, 0, 0x10000
	s_mul_i32 s6, s2, 0x1800000
	s_mul_hi_i32 s7, s2, 0x1800000
	s_add_u32 s25, s56, s6
	s_addc_u32 s26, s57, s7
	s_lshl_b32 s2, s4, 3
	s_and_b32 s23, s2, 0x380
	s_lshl_b32 s2, s23, 1
	s_add_u32 s4, s25, s2
	s_addc_u32 s5, s26, 0
	s_add_u32 s2, s4, 0x1000
	v_lshl_add_u32 v204, v0, 4, s3
	s_addc_u32 s3, s5, 0
	s_add_u32 s4, s4, 0x61000
	s_addc_u32 s5, s5, 0
	s_add_u32 s27, s49, s6
	v_bfe_u32 v203, v0, 5, 1
	s_addc_u32 s28, s50, s7
	s_or_b32 s6, s6, s8
	v_mad_i32_i24 v3, v185, s87, v3
	v_lshlrev_b32_e32 v182, 4, v203
	v_mov_b32_e32 v183, v1
	s_add_u32 s6, s75, s6
	v_lshl_add_u64 v[186:187], v[2:3], 0, v[182:183]
	s_addc_u32 s7, s76, s7
	s_mov_b32 s10, 0
	s_mov_b64 s[8:9], -1
	s_branch .LBB0_800
